# SwiGLU epilogue H stores write-through (sc1)
# baseline (speedup 1.0000x reference)
; __device__ __forceinline__ float sigmoidf_(float v) { return __builtin_amdgcn_rcpf(1.f + __builtin_amdgcn_exp2f(-v * LOG2E)); }
; __device__ __forceinline__ v4u pack8(f32x4 a, f32x4 b) { v4u r; r.x = cvt_pk_bf16(a[0], a[1]); r.y = cvt_pk_bf16(a[2], a[3]); r.z = cvt_pk_bf16(b[0], b[1]); r.w = cvt_pk_bf16(b[2], b[3]); return r; }
;     __device__ __forceinline__ void operator()(const f32x4 (&acc)[2][2][4][2], const Unit& u, int wr, int wc, int fr, int fq) const {
;         const int row0 = u.pm * 256 + wr * 64 + fr, col0 = u.pn * 128 + wc * 32 + 8 * fq;
; #pragma unroll
;         for (int ai = 0; ai < 2; ++ai)
; #pragma unroll
;             for (int m = 0; m < 4; ++m) {
;                 const int row = row0 + ai * 128 + m * 16;
;                 float sq = 0.f;
; #pragma unroll
;                 for (int k = 0; k < 4; ++k) { const f32x4 p = *(const f32x4*)(ss1 + (size_t)row * 16 + 4 * k); sq += (p[0] + p[1]) + (p[2] + p[3]); }
;                 const float rs = rsqrtf(sq * (1.f / 1024.f) + EPS);
;                 f32x4 o[2];
; #pragma unroll
;                 for (int n = 0; n < 2; ++n) {
;                     const f32x4 g = acc[ai][0][m][n] * rs, up = acc[ai][1][m][n] * rs;
; #pragma unroll
;                     for (int j = 0; j < 4; ++j) o[n][j] = g[j] * sigmoidf_(g[j]) * up[j];
;                 }
;                 *(v4u*)(H + (size_t)row * FF + col0) = pack8(o[0], o[1]);
;             }
.LBB0_1481:
	v_lshl_add_u32 v148, s8, 8, v150
	v_ashrrev_i32_e32 v149, 31, v148
	v_lshlrev_b64 v[144:145], 6, v[148:149]
	v_lshl_add_u64 v[144:145], s[18:19], 0, v[144:145]
	global_load_dwordx4 v[162:165], v[144:145], off
	global_load_dwordx4 v[166:169], v[144:145], off offset:16
	global_load_dwordx4 v[170:173], v[144:145], off offset:32
	global_load_dwordx4 v[174:177], v[144:145], off offset:48
	v_lshl_or_b32 v146, s9, 7, v152
	v_mov_b64_e32 v[144:145], s[28:29]
	v_ashrrev_i32_e32 v147, 31, v146
	v_mad_i64_i32 v[178:179], s[8:9], v148, s58, v[144:145]
	v_lshlrev_b64 v[146:147], 1, v[146:147]
	v_or_b32_e32 v180, 16, v148
	v_ashrrev_i32_e32 v181, 31, v180
	s_waitcnt vmcnt(0)
	v_mov_b32_e32 v182, v163
	v_mov_b32_e32 v183, v164
	v_mov_b32_e32 v163, v165
	v_mov_b32_e32 v164, v167
	v_mov_b32_e32 v165, v168
	v_mov_b32_e32 v167, v169
	v_pk_add_f32 v[162:163], v[182:183], v[162:163]
	v_pk_add_f32 v[164:165], v[164:165], v[166:167]
	v_add_f32_e32 v149, v162, v163
	v_pk_add_f32 v[162:163], v[164:165], v[164:165] op_sel:[0,1] op_sel_hi:[1,0]
	v_add_f32_e32 v168, v170, v171
	v_add_f32_e32 v170, v172, v173
	v_mov_b32_e32 v173, v174
	v_mov_b32_e32 v169, v176
	v_mov_b32_e32 v171, v177
	v_add_f32_e32 v172, 0, v149
	v_mov_b32_e32 v163, v175
	v_pk_add_f32 v[166:167], v[168:169], v[170:171]
	v_pk_add_f32 v[162:163], v[172:173], v[162:163]
	v_lshlrev_b64 v[164:165], 6, v[180:181]
	v_pk_add_f32 v[162:163], v[162:163], v[166:167]
	v_lshl_add_u64 v[164:165], s[18:19], 0, v[164:165]
	v_add_f32_e32 v149, v162, v163
	v_fmamk_f32 v149, v149, 0x3a800000, v161
	v_mul_f32_e32 v162, 0x4b800000, v149
	v_cmp_gt_f32_e32 vcc, s57, v149
	s_nop 1
	v_cndmask_b32_e32 v149, v149, v162, vcc
	v_rsq_f32_e32 v149, v149
	v_lshl_add_u64 v[162:163], v[178:179], 0, v[146:147]
	v_mul_f32_e32 v166, 0x45800000, v149
	v_cndmask_b32_e32 v166, v149, v166, vcc
	v_pk_mul_f32 v[124:125], v[124:125], v[166:167] op_sel_hi:[1,0]
	v_pk_mul_f32 v[126:127], v[126:127], v[166:167] op_sel_hi:[1,0]
	v_pk_mul_f32 v[120:121], v[120:121], v[166:167] op_sel_hi:[1,0]
	v_pk_mul_f32 v[122:123], v[122:123], v[166:167] op_sel_hi:[1,0]
	v_pk_mul_f32 v[116:117], v[116:117], v[166:167] op_sel_hi:[1,0]
	v_pk_mul_f32 v[118:119], v[118:119], v[166:167] op_sel_hi:[1,0]
	v_pk_mul_f32 v[112:113], v[112:113], v[166:167] op_sel_hi:[1,0]
	v_pk_mul_f32 v[114:115], v[114:115], v[166:167] op_sel_hi:[1,0]
	v_mul_f32_e32 v149, 0xbfb8aa3b, v124
	v_mul_f32_e32 v166, 0xbfb8aa3b, v125
	v_mul_f32_e32 v167, 0xbfb8aa3b, v126
	v_mul_f32_e32 v168, 0xbfb8aa3b, v127
	v_mul_f32_e32 v169, 0xbfb8aa3b, v120
	v_mul_f32_e32 v170, 0xbfb8aa3b, v121
	v_mul_f32_e32 v171, 0xbfb8aa3b, v122
	v_mul_f32_e32 v172, 0xbfb8aa3b, v123
	v_exp_f32_e32 v149, v149
	v_exp_f32_e32 v166, v166
	v_exp_f32_e32 v167, v167
	v_exp_f32_e32 v168, v168
	v_exp_f32_e32 v169, v169
	v_exp_f32_e32 v170, v170
	v_exp_f32_e32 v171, v171
	v_exp_f32_e32 v172, v172
	v_add_f32_e32 v149, 1.0, v149
	v_add_f32_e32 v173, 1.0, v166
	v_add_f32_e32 v174, 1.0, v167
	v_add_f32_e32 v175, 1.0, v168
	v_add_f32_e32 v176, 1.0, v169
	v_add_f32_e32 v177, 1.0, v170
	v_add_f32_e32 v178, 1.0, v171
	v_add_f32_e32 v179, 1.0, v172
	v_rcp_f32_e32 v166, v149
	v_rcp_f32_e32 v167, v173
	v_rcp_f32_e32 v168, v174
	v_rcp_f32_e32 v169, v175
	v_rcp_f32_e32 v170, v176
	v_rcp_f32_e32 v171, v177
	v_rcp_f32_e32 v172, v178
	v_rcp_f32_e32 v173, v179
	v_pk_mul_f32 v[124:125], v[124:125], v[166:167]
	v_pk_mul_f32 v[126:127], v[126:127], v[168:169]
	v_pk_mul_f32 v[120:121], v[120:121], v[170:171]
	v_pk_mul_f32 v[122:123], v[122:123], v[172:173]
	v_pk_mul_f32 v[116:117], v[116:117], v[124:125]
	v_pk_mul_f32 v[118:119], v[118:119], v[126:127]
	v_pk_mul_f32 v[120:121], v[112:113], v[120:121]
	v_pk_mul_f32 v[122:123], v[114:115], v[122:123]
	v_cvt_pk_bf16_f32 v112, v116, v117
	v_cvt_pk_bf16_f32 v113, v118, v119
	v_cvt_pk_bf16_f32 v114, v120, v121
	v_cvt_pk_bf16_f32 v115, v122, v123
	global_store_dwordx4 v[162:163], v[112:115], off sc1
	global_load_dwordx4 v[112:115], v[164:165], off
	s_nop 0
	global_load_dwordx4 v[116:119], v[164:165], off offset:16
	global_load_dwordx4 v[120:123], v[164:165], off offset:32
	global_load_dwordx4 v[124:127], v[164:165], off offset:48
	v_or_b32_e32 v162, 32, v148
	v_mad_i64_i32 v[164:165], s[8:9], v180, s58, v[144:145]
	v_ashrrev_i32_e32 v163, 31, v162
	s_waitcnt vmcnt(3)
	v_mov_b32_e32 v166, v113
	v_mov_b32_e32 v167, v114
	v_mov_b32_e32 v113, v115
	s_waitcnt vmcnt(2)
	v_mov_b32_e32 v114, v117
	v_mov_b32_e32 v115, v118
	v_mov_b32_e32 v117, v119
	s_waitcnt vmcnt(1)
	v_add_f32_e32 v118, v120, v121
	v_add_f32_e32 v120, v122, v123
	s_waitcnt vmcnt(0)
; __device__ __forceinline__ float sigmoidf_(float v) { return __builtin_amdgcn_rcpf(1.f + __builtin_amdgcn_exp2f(-v * LOG2E)); }
; __device__ __forceinline__ v4u pack8(f32x4 a, f32x4 b) { v4u r; r.x = cvt_pk_bf16(a[0], a[1]); r.y = cvt_pk_bf16(a[2], a[3]); r.z = cvt_pk_bf16(b[0], b[1]); r.w = cvt_pk_bf16(b[2], b[3]); return r; }
;     __device__ __forceinline__ void operator()(const f32x4 (&acc)[2][2][4][2], const Unit& u, int wr, int wc, int fr, int fq) const {
;     ...
;         for (int ai = 0; ai < 2; ++ai)
; #pragma unroll
;             for (int m = 0; m < 4; ++m) {
;                 const int row = row0 + ai * 128 + m * 16;
;                 float sq = 0.f;
; #pragma unroll
;                 for (int k = 0; k < 4; ++k) { const f32x4 p = *(const f32x4*)(ss1 + (size_t)row * 16 + 4 * k); sq += (p[0] + p[1]) + (p[2] + p[3]); }
;                 const float rs = rsqrtf(sq * (1.f / 1024.f) + EPS);
;                 f32x4 o[2];
; #pragma unroll
;                 for (int n = 0; n < 2; ++n) {
;                     const f32x4 g = acc[ai][0][m][n] * rs, up = acc[ai][1][m][n] * rs;
; #pragma unroll
;                     for (int j = 0; j < 4; ++j) o[n][j] = g[j] * sigmoidf_(g[j]) * up[j];
;                 }
;                 *(v4u*)(H + (size_t)row * FF + col0) = pack8(o[0], o[1]);
;             }
	v_mov_b32_e32 v119, v126
	v_mov_b32_e32 v121, v127
	v_pk_add_f32 v[112:113], v[166:167], v[112:113]
	v_pk_add_f32 v[114:115], v[114:115], v[116:117]
	v_pk_add_f32 v[116:117], v[118:119], v[120:121]
	v_add_f32_e32 v118, v112, v113
	v_pk_add_f32 v[112:113], v[114:115], v[114:115] op_sel:[0,1] op_sel_hi:[1,0]
	v_mov_b32_e32 v123, v124
	v_add_f32_e32 v122, 0, v118
	v_mov_b32_e32 v113, v125
	v_pk_add_f32 v[112:113], v[122:123], v[112:113]
	v_lshlrev_b64 v[114:115], 6, v[162:163]
	v_pk_add_f32 v[112:113], v[112:113], v[116:117]
	v_lshl_add_u64 v[114:115], s[18:19], 0, v[114:115]
	v_add_f32_e32 v112, v112, v113
	v_fmamk_f32 v112, v112, 0x3a800000, v161
	v_mul_f32_e32 v113, 0x4b800000, v112
	v_cmp_gt_f32_e32 vcc, s57, v112
	s_nop 1
	v_cndmask_b32_e32 v112, v112, v113, vcc
	v_rsq_f32_e32 v116, v112
	v_lshl_add_u64 v[112:113], v[164:165], 0, v[146:147]
	v_mul_f32_e32 v117, 0x45800000, v116
	v_cndmask_b32_e32 v116, v116, v117, vcc
	v_pk_mul_f32 v[108:109], v[108:109], v[116:117] op_sel_hi:[1,0]
	v_pk_mul_f32 v[110:111], v[110:111], v[116:117] op_sel_hi:[1,0]
	v_pk_mul_f32 v[104:105], v[104:105], v[116:117] op_sel_hi:[1,0]
	v_pk_mul_f32 v[106:107], v[106:107], v[116:117] op_sel_hi:[1,0]
	v_pk_mul_f32 v[100:101], v[100:101], v[116:117] op_sel_hi:[1,0]
	v_pk_mul_f32 v[102:103], v[102:103], v[116:117] op_sel_hi:[1,0]
	v_pk_mul_f32 v[96:97], v[96:97], v[116:117] op_sel_hi:[1,0]
	v_pk_mul_f32 v[98:99], v[98:99], v[116:117] op_sel_hi:[1,0]
	v_mul_f32_e32 v116, 0xbfb8aa3b, v108
	v_mul_f32_e32 v117, 0xbfb8aa3b, v109
	v_mul_f32_e32 v118, 0xbfb8aa3b, v110
	v_mul_f32_e32 v119, 0xbfb8aa3b, v111
	v_mul_f32_e32 v120, 0xbfb8aa3b, v104
	v_mul_f32_e32 v121, 0xbfb8aa3b, v105
	v_mul_f32_e32 v122, 0xbfb8aa3b, v106
	v_mul_f32_e32 v123, 0xbfb8aa3b, v107
	v_exp_f32_e32 v116, v116
	v_exp_f32_e32 v117, v117
	v_exp_f32_e32 v118, v118
	v_exp_f32_e32 v119, v119
	v_exp_f32_e32 v120, v120
	v_exp_f32_e32 v121, v121
	v_exp_f32_e32 v122, v122
	v_exp_f32_e32 v123, v123
	v_add_f32_e32 v116, 1.0, v116
	v_add_f32_e32 v117, 1.0, v117
	v_add_f32_e32 v118, 1.0, v118
	v_add_f32_e32 v119, 1.0, v119
	v_add_f32_e32 v120, 1.0, v120
	v_add_f32_e32 v121, 1.0, v121
	v_add_f32_e32 v122, 1.0, v122
	v_add_f32_e32 v123, 1.0, v123
	v_rcp_f32_e32 v116, v116
	v_rcp_f32_e32 v117, v117
	v_rcp_f32_e32 v118, v118
	v_rcp_f32_e32 v119, v119
	v_rcp_f32_e32 v120, v120
	v_rcp_f32_e32 v121, v121
	v_rcp_f32_e32 v122, v122
	v_rcp_f32_e32 v123, v123
	v_pk_mul_f32 v[108:109], v[108:109], v[116:117]
	v_pk_mul_f32 v[110:111], v[110:111], v[118:119]
	v_pk_mul_f32 v[104:105], v[104:105], v[120:121]
	v_pk_mul_f32 v[106:107], v[106:107], v[122:123]
	v_pk_mul_f32 v[100:101], v[100:101], v[108:109]
	v_pk_mul_f32 v[102:103], v[102:103], v[110:111]
	v_pk_mul_f32 v[104:105], v[96:97], v[104:105]
	v_pk_mul_f32 v[106:107], v[98:99], v[106:107]
	v_cvt_pk_bf16_f32 v96, v100, v101
	v_cvt_pk_bf16_f32 v97, v102, v103
	v_cvt_pk_bf16_f32 v98, v104, v105
	v_cvt_pk_bf16_f32 v99, v106, v107
	global_store_dwordx4 v[112:113], v[96:99], off sc1
	global_load_dwordx4 v[96:99], v[114:115], off
	s_nop 0
	global_load_dwordx4 v[100:103], v[114:115], off offset:16
	global_load_dwordx4 v[104:107], v[114:115], off offset:32
	global_load_dwordx4 v[108:111], v[114:115], off offset:48
	v_or_b32_e32 v112, 48, v148
	v_mad_i64_i32 v[114:115], s[8:9], v162, s58, v[144:145]
	v_ashrrev_i32_e32 v113, 31, v112
	s_waitcnt vmcnt(3)
	v_mov_b32_e32 v116, v97
	v_mov_b32_e32 v117, v98
	v_mov_b32_e32 v97, v99
	s_waitcnt vmcnt(2)
	v_mov_b32_e32 v98, v101
	v_mov_b32_e32 v99, v102
	v_mov_b32_e32 v101, v103
	s_waitcnt vmcnt(1)
	v_add_f32_e32 v102, v104, v105
	v_add_f32_e32 v104, v106, v107
	s_waitcnt vmcnt(0)
	v_mov_b32_e32 v103, v110
	v_mov_b32_e32 v105, v111
	v_pk_add_f32 v[96:97], v[116:117], v[96:97]
	v_pk_add_f32 v[98:99], v[98:99], v[100:101]
	v_pk_add_f32 v[100:101], v[102:103], v[104:105]
	v_add_f32_e32 v102, v96, v97
	v_pk_add_f32 v[96:97], v[98:99], v[98:99] op_sel:[0,1] op_sel_hi:[1,0]
	v_mov_b32_e32 v107, v108
	v_add_f32_e32 v106, 0, v102
	v_mov_b32_e32 v97, v109
	v_pk_add_f32 v[96:97], v[106:107], v[96:97]
	v_lshlrev_b64 v[98:99], 6, v[112:113]
	v_pk_add_f32 v[96:97], v[96:97], v[100:101]
	v_lshl_add_u64 v[98:99], s[18:19], 0, v[98:99]
	v_add_f32_e32 v96, v96, v97
	v_fmamk_f32 v96, v96, 0x3a800000, v161
	v_mul_f32_e32 v97, 0x4b800000, v96
	v_cmp_gt_f32_e32 vcc, s57, v96
	s_nop 1
	v_cndmask_b32_e32 v96, v96, v97, vcc
	v_rsq_f32_e32 v100, v96
	v_lshl_add_u64 v[96:97], v[114:115], 0, v[146:147]
	v_mul_f32_e32 v101, 0x45800000, v100
	v_cndmask_b32_e32 v100, v100, v101, vcc
	v_pk_mul_f32 v[92:93], v[92:93], v[100:101] op_sel_hi:[1,0]
	v_pk_mul_f32 v[94:95], v[94:95], v[100:101] op_sel_hi:[1,0]
	v_pk_mul_f32 v[88:89], v[88:89], v[100:101] op_sel_hi:[1,0]
	v_pk_mul_f32 v[90:91], v[90:91], v[100:101] op_sel_hi:[1,0]
	v_pk_mul_f32 v[84:85], v[84:85], v[100:101] op_sel_hi:[1,0]
	v_pk_mul_f32 v[86:87], v[86:87], v[100:101] op_sel_hi:[1,0]
	v_pk_mul_f32 v[80:81], v[80:81], v[100:101] op_sel_hi:[1,0]
	v_pk_mul_f32 v[82:83], v[82:83], v[100:101] op_sel_hi:[1,0]
	v_mul_f32_e32 v100, 0xbfb8aa3b, v92
	v_mul_f32_e32 v101, 0xbfb8aa3b, v93
	v_mul_f32_e32 v102, 0xbfb8aa3b, v94
	v_mul_f32_e32 v103, 0xbfb8aa3b, v95
	v_mul_f32_e32 v104, 0xbfb8aa3b, v88
	v_mul_f32_e32 v105, 0xbfb8aa3b, v89
	v_mul_f32_e32 v106, 0xbfb8aa3b, v90
	v_mul_f32_e32 v107, 0xbfb8aa3b, v91
	v_exp_f32_e32 v100, v100
	v_exp_f32_e32 v101, v101
	v_exp_f32_e32 v102, v102
	v_exp_f32_e32 v103, v103
	v_exp_f32_e32 v104, v104
	v_exp_f32_e32 v105, v105
	v_exp_f32_e32 v106, v106
	v_exp_f32_e32 v107, v107
	v_add_f32_e32 v100, 1.0, v100
	v_add_f32_e32 v101, 1.0, v101
	v_add_f32_e32 v102, 1.0, v102
	v_add_f32_e32 v103, 1.0, v103
	v_add_f32_e32 v104, 1.0, v104
	v_add_f32_e32 v105, 1.0, v105
	v_add_f32_e32 v106, 1.0, v106
	v_add_f32_e32 v107, 1.0, v107
	v_rcp_f32_e32 v100, v100
	v_rcp_f32_e32 v101, v101
	v_rcp_f32_e32 v102, v102
	v_rcp_f32_e32 v103, v103
	v_rcp_f32_e32 v104, v104
	v_rcp_f32_e32 v105, v105
	v_rcp_f32_e32 v106, v106
	v_rcp_f32_e32 v107, v107
	v_pk_mul_f32 v[92:93], v[92:93], v[100:101]
	v_pk_mul_f32 v[94:95], v[94:95], v[102:103]
	v_pk_mul_f32 v[88:89], v[88:89], v[104:105]
	v_pk_mul_f32 v[90:91], v[90:91], v[106:107]
	v_pk_mul_f32 v[84:85], v[84:85], v[92:93]
	v_pk_mul_f32 v[86:87], v[86:87], v[94:95]
	v_pk_mul_f32 v[88:89], v[80:81], v[88:89]
	v_pk_mul_f32 v[90:91], v[82:83], v[90:91]
	v_cvt_pk_bf16_f32 v80, v84, v85
	v_cvt_pk_bf16_f32 v81, v86, v87
	v_cvt_pk_bf16_f32 v82, v88, v89
	v_cvt_pk_bf16_f32 v83, v90, v91
	global_store_dwordx4 v[96:97], v[80:83], off sc1
	global_load_dwordx4 v[80:83], v[98:99], off
	s_nop 0
	global_load_dwordx4 v[84:87], v[98:99], off offset:16
	global_load_dwordx4 v[88:91], v[98:99], off offset:32
	global_load_dwordx4 v[92:95], v[98:99], off offset:48
	v_add_u32_e32 v96, 0x80, v148
	v_mad_i64_i32 v[98:99], s[8:9], v112, s58, v[144:145]
	v_ashrrev_i32_e32 v97, 31, v96
	s_waitcnt vmcnt(3)
; __device__ __forceinline__ float sigmoidf_(float v) { return __builtin_amdgcn_rcpf(1.f + __builtin_amdgcn_exp2f(-v * LOG2E)); }
; __device__ __forceinline__ v4u pack8(f32x4 a, f32x4 b) { v4u r; r.x = cvt_pk_bf16(a[0], a[1]); r.y = cvt_pk_bf16(a[2], a[3]); r.z = cvt_pk_bf16(b[0], b[1]); r.w = cvt_pk_bf16(b[2], b[3]); return r; }
;     __device__ __forceinline__ void operator()(const f32x4 (&acc)[2][2][4][2], const Unit& u, int wr, int wc, int fr, int fq) const {
;     ...
;         for (int ai = 0; ai < 2; ++ai)
; #pragma unroll
;             for (int m = 0; m < 4; ++m) {
;                 const int row = row0 + ai * 128 + m * 16;
;                 float sq = 0.f;
; #pragma unroll
;                 for (int k = 0; k < 4; ++k) { const f32x4 p = *(const f32x4*)(ss1 + (size_t)row * 16 + 4 * k); sq += (p[0] + p[1]) + (p[2] + p[3]); }
;                 const float rs = rsqrtf(sq * (1.f / 1024.f) + EPS);
;                 f32x4 o[2];
; #pragma unroll
;                 for (int n = 0; n < 2; ++n) {
;                     const f32x4 g = acc[ai][0][m][n] * rs, up = acc[ai][1][m][n] * rs;
; #pragma unroll
;                     for (int j = 0; j < 4; ++j) o[n][j] = g[j] * sigmoidf_(g[j]) * up[j];
;                 }
;                 *(v4u*)(H + (size_t)row * FF + col0) = pack8(o[0], o[1]);
;             }
	v_mov_b32_e32 v100, v81
	v_mov_b32_e32 v101, v82
	v_mov_b32_e32 v81, v83
	s_waitcnt vmcnt(2)
	v_mov_b32_e32 v82, v85
	v_mov_b32_e32 v83, v86
	v_mov_b32_e32 v85, v87
	s_waitcnt vmcnt(1)
	v_add_f32_e32 v86, v88, v89
	v_add_f32_e32 v88, v90, v91
	s_waitcnt vmcnt(0)
	v_mov_b32_e32 v87, v94
	v_mov_b32_e32 v89, v95
	v_pk_add_f32 v[80:81], v[100:101], v[80:81]
	v_pk_add_f32 v[82:83], v[82:83], v[84:85]
	v_pk_add_f32 v[84:85], v[86:87], v[88:89]
	v_add_f32_e32 v86, v80, v81
	v_pk_add_f32 v[80:81], v[82:83], v[82:83] op_sel:[0,1] op_sel_hi:[1,0]
	v_mov_b32_e32 v91, v92
	v_add_f32_e32 v90, 0, v86
	v_mov_b32_e32 v81, v93
	v_pk_add_f32 v[80:81], v[90:91], v[80:81]
	v_lshlrev_b64 v[82:83], 6, v[96:97]
	v_pk_add_f32 v[80:81], v[80:81], v[84:85]
	v_lshl_add_u64 v[82:83], s[18:19], 0, v[82:83]
	v_add_f32_e32 v80, v80, v81
	v_fmamk_f32 v80, v80, 0x3a800000, v161
	v_mul_f32_e32 v81, 0x4b800000, v80
	v_cmp_gt_f32_e32 vcc, s57, v80
	s_nop 1
	v_cndmask_b32_e32 v80, v80, v81, vcc
	v_rsq_f32_e32 v84, v80
	v_lshl_add_u64 v[80:81], v[98:99], 0, v[146:147]
	v_mul_f32_e32 v85, 0x45800000, v84
	v_cndmask_b32_e32 v84, v84, v85, vcc
	v_pk_mul_f32 v[76:77], v[76:77], v[84:85] op_sel_hi:[1,0]
	v_pk_mul_f32 v[78:79], v[78:79], v[84:85] op_sel_hi:[1,0]
	v_pk_mul_f32 v[72:73], v[72:73], v[84:85] op_sel_hi:[1,0]
	v_pk_mul_f32 v[74:75], v[74:75], v[84:85] op_sel_hi:[1,0]
	v_pk_mul_f32 v[68:69], v[68:69], v[84:85] op_sel_hi:[1,0]
	v_pk_mul_f32 v[70:71], v[70:71], v[84:85] op_sel_hi:[1,0]
	v_pk_mul_f32 v[64:65], v[64:65], v[84:85] op_sel_hi:[1,0]
	v_pk_mul_f32 v[66:67], v[66:67], v[84:85] op_sel_hi:[1,0]
	v_mul_f32_e32 v84, 0xbfb8aa3b, v76
	v_mul_f32_e32 v85, 0xbfb8aa3b, v77
	v_mul_f32_e32 v86, 0xbfb8aa3b, v78
	v_mul_f32_e32 v87, 0xbfb8aa3b, v79
	v_mul_f32_e32 v88, 0xbfb8aa3b, v72
	v_mul_f32_e32 v89, 0xbfb8aa3b, v73
	v_mul_f32_e32 v90, 0xbfb8aa3b, v74
	v_mul_f32_e32 v91, 0xbfb8aa3b, v75
	v_exp_f32_e32 v84, v84
	v_exp_f32_e32 v85, v85
	v_exp_f32_e32 v86, v86
	v_exp_f32_e32 v87, v87
	v_exp_f32_e32 v88, v88
	v_exp_f32_e32 v89, v89
	v_exp_f32_e32 v90, v90
	v_exp_f32_e32 v91, v91
	v_add_f32_e32 v84, 1.0, v84
	v_add_f32_e32 v85, 1.0, v85
	v_add_f32_e32 v86, 1.0, v86
	v_add_f32_e32 v87, 1.0, v87
	v_add_f32_e32 v88, 1.0, v88
	v_add_f32_e32 v89, 1.0, v89
	v_add_f32_e32 v90, 1.0, v90
	v_add_f32_e32 v91, 1.0, v91
	v_rcp_f32_e32 v84, v84
	v_rcp_f32_e32 v85, v85
	v_rcp_f32_e32 v86, v86
	v_rcp_f32_e32 v87, v87
	v_rcp_f32_e32 v88, v88
	v_rcp_f32_e32 v89, v89
	v_rcp_f32_e32 v90, v90
	v_rcp_f32_e32 v91, v91
	v_pk_mul_f32 v[76:77], v[76:77], v[84:85]
	v_pk_mul_f32 v[78:79], v[78:79], v[86:87]
	v_pk_mul_f32 v[72:73], v[72:73], v[88:89]
	v_pk_mul_f32 v[74:75], v[74:75], v[90:91]
	v_pk_mul_f32 v[68:69], v[68:69], v[76:77]
	v_pk_mul_f32 v[70:71], v[70:71], v[78:79]
	v_pk_mul_f32 v[72:73], v[64:65], v[72:73]
	v_pk_mul_f32 v[74:75], v[66:67], v[74:75]
	v_cvt_pk_bf16_f32 v64, v68, v69
	v_cvt_pk_bf16_f32 v65, v70, v71
	v_cvt_pk_bf16_f32 v66, v72, v73
	v_cvt_pk_bf16_f32 v67, v74, v75
	global_store_dwordx4 v[80:81], v[64:67], off sc1
	global_load_dwordx4 v[64:67], v[82:83], off
	s_nop 0
	global_load_dwordx4 v[68:71], v[82:83], off offset:16
	global_load_dwordx4 v[72:75], v[82:83], off offset:32
	global_load_dwordx4 v[76:79], v[82:83], off offset:48
	v_add_u32_e32 v80, 0x90, v148
	v_mad_i64_i32 v[82:83], s[8:9], v96, s58, v[144:145]
	v_ashrrev_i32_e32 v81, 31, v80
	s_waitcnt vmcnt(3)
	v_mov_b32_e32 v84, v65
	v_mov_b32_e32 v85, v66
	v_mov_b32_e32 v65, v67
	s_waitcnt vmcnt(2)
	v_mov_b32_e32 v66, v69
	v_mov_b32_e32 v67, v70
	v_mov_b32_e32 v69, v71
	s_waitcnt vmcnt(1)
	v_add_f32_e32 v70, v72, v73
	v_add_f32_e32 v72, v74, v75
	s_waitcnt vmcnt(0)
	v_mov_b32_e32 v71, v78
	v_mov_b32_e32 v73, v79
	v_pk_add_f32 v[64:65], v[84:85], v[64:65]
	v_pk_add_f32 v[66:67], v[66:67], v[68:69]
	v_pk_add_f32 v[68:69], v[70:71], v[72:73]
	v_add_f32_e32 v70, v64, v65
	v_pk_add_f32 v[64:65], v[66:67], v[66:67] op_sel:[0,1] op_sel_hi:[1,0]
	v_mov_b32_e32 v75, v76
	v_add_f32_e32 v74, 0, v70
	v_mov_b32_e32 v65, v77
	v_pk_add_f32 v[64:65], v[74:75], v[64:65]
	v_lshlrev_b64 v[66:67], 6, v[80:81]
	v_pk_add_f32 v[64:65], v[64:65], v[68:69]
	v_lshl_add_u64 v[66:67], s[18:19], 0, v[66:67]
	v_add_f32_e32 v64, v64, v65
	v_fmamk_f32 v64, v64, 0x3a800000, v161
	v_mul_f32_e32 v65, 0x4b800000, v64
	v_cmp_gt_f32_e32 vcc, s57, v64
	s_nop 1
	v_cndmask_b32_e32 v64, v64, v65, vcc
	v_rsq_f32_e32 v68, v64
	v_lshl_add_u64 v[64:65], v[82:83], 0, v[146:147]
	v_mul_f32_e32 v69, 0x45800000, v68
	v_cndmask_b32_e32 v68, v68, v69, vcc
	v_pk_mul_f32 v[60:61], v[60:61], v[68:69] op_sel_hi:[1,0]
	v_pk_mul_f32 v[62:63], v[62:63], v[68:69] op_sel_hi:[1,0]
	v_pk_mul_f32 v[56:57], v[56:57], v[68:69] op_sel_hi:[1,0]
	v_pk_mul_f32 v[58:59], v[58:59], v[68:69] op_sel_hi:[1,0]
	v_pk_mul_f32 v[52:53], v[52:53], v[68:69] op_sel_hi:[1,0]
	v_pk_mul_f32 v[54:55], v[54:55], v[68:69] op_sel_hi:[1,0]
	v_pk_mul_f32 v[48:49], v[48:49], v[68:69] op_sel_hi:[1,0]
	v_pk_mul_f32 v[50:51], v[50:51], v[68:69] op_sel_hi:[1,0]
	v_mul_f32_e32 v68, 0xbfb8aa3b, v60
	v_mul_f32_e32 v69, 0xbfb8aa3b, v61
	v_mul_f32_e32 v70, 0xbfb8aa3b, v62
	v_mul_f32_e32 v71, 0xbfb8aa3b, v63
	v_mul_f32_e32 v72, 0xbfb8aa3b, v56
	v_mul_f32_e32 v73, 0xbfb8aa3b, v57
	v_mul_f32_e32 v74, 0xbfb8aa3b, v58
	v_mul_f32_e32 v75, 0xbfb8aa3b, v59
	v_exp_f32_e32 v68, v68
	v_exp_f32_e32 v69, v69
	v_exp_f32_e32 v70, v70
	v_exp_f32_e32 v71, v71
	v_exp_f32_e32 v72, v72
	v_exp_f32_e32 v73, v73
	v_exp_f32_e32 v74, v74
	v_exp_f32_e32 v75, v75
	v_add_f32_e32 v68, 1.0, v68
	v_add_f32_e32 v69, 1.0, v69
	v_add_f32_e32 v70, 1.0, v70
	v_add_f32_e32 v71, 1.0, v71
	v_add_f32_e32 v72, 1.0, v72
	v_add_f32_e32 v73, 1.0, v73
	v_add_f32_e32 v74, 1.0, v74
	v_add_f32_e32 v75, 1.0, v75
	v_rcp_f32_e32 v68, v68
	v_rcp_f32_e32 v69, v69
	v_rcp_f32_e32 v70, v70
	v_rcp_f32_e32 v71, v71
	v_rcp_f32_e32 v72, v72
	v_rcp_f32_e32 v73, v73
	v_rcp_f32_e32 v74, v74
	v_rcp_f32_e32 v75, v75
	v_pk_mul_f32 v[60:61], v[60:61], v[68:69]
	v_pk_mul_f32 v[62:63], v[62:63], v[70:71]
	v_pk_mul_f32 v[56:57], v[56:57], v[72:73]
	v_pk_mul_f32 v[58:59], v[58:59], v[74:75]
	v_pk_mul_f32 v[52:53], v[52:53], v[60:61]
	v_pk_mul_f32 v[54:55], v[54:55], v[62:63]
	v_pk_mul_f32 v[56:57], v[48:49], v[56:57]
	v_pk_mul_f32 v[58:59], v[50:51], v[58:59]
	v_cvt_pk_bf16_f32 v48, v52, v53
	v_cvt_pk_bf16_f32 v49, v54, v55
	v_cvt_pk_bf16_f32 v50, v56, v57
	v_cvt_pk_bf16_f32 v51, v58, v59
	global_store_dwordx4 v[64:65], v[48:51], off sc1
	global_load_dwordx4 v[48:51], v[66:67], off
	s_nop 0
	global_load_dwordx4 v[52:55], v[66:67], off offset:16
	global_load_dwordx4 v[56:59], v[66:67], off offset:32
	global_load_dwordx4 v[60:63], v[66:67], off offset:48
	v_add_u32_e32 v64, 0xa0, v148
	v_mad_i64_i32 v[66:67], s[8:9], v80, s58, v[144:145]
	v_ashrrev_i32_e32 v65, 31, v64
	s_waitcnt vmcnt(3)
; __device__ __forceinline__ float sigmoidf_(float v) { return __builtin_amdgcn_rcpf(1.f + __builtin_amdgcn_exp2f(-v * LOG2E)); }
; __device__ __forceinline__ v4u pack8(f32x4 a, f32x4 b) { v4u r; r.x = cvt_pk_bf16(a[0], a[1]); r.y = cvt_pk_bf16(a[2], a[3]); r.z = cvt_pk_bf16(b[0], b[1]); r.w = cvt_pk_bf16(b[2], b[3]); return r; }
;     __device__ __forceinline__ void operator()(const f32x4 (&acc)[2][2][4][2], const Unit& u, int wr, int wc, int fr, int fq) const {
;     ...
;         for (int ai = 0; ai < 2; ++ai)
; #pragma unroll
;             for (int m = 0; m < 4; ++m) {
;                 const int row = row0 + ai * 128 + m * 16;
;                 float sq = 0.f;
; #pragma unroll
;                 for (int k = 0; k < 4; ++k) { const f32x4 p = *(const f32x4*)(ss1 + (size_t)row * 16 + 4 * k); sq += (p[0] + p[1]) + (p[2] + p[3]); }
;                 const float rs = rsqrtf(sq * (1.f / 1024.f) + EPS);
;                 f32x4 o[2];
; #pragma unroll
;                 for (int n = 0; n < 2; ++n) {
;                     const f32x4 g = acc[ai][0][m][n] * rs, up = acc[ai][1][m][n] * rs;
; #pragma unroll
;                     for (int j = 0; j < 4; ++j) o[n][j] = g[j] * sigmoidf_(g[j]) * up[j];
;                 }
;                 *(v4u*)(H + (size_t)row * FF + col0) = pack8(o[0], o[1]);
;             }
	v_mov_b32_e32 v68, v49
	v_mov_b32_e32 v69, v50
	v_mov_b32_e32 v49, v51
	s_waitcnt vmcnt(2)
	v_mov_b32_e32 v50, v53
	v_mov_b32_e32 v51, v54
	v_mov_b32_e32 v53, v55
	s_waitcnt vmcnt(1)
	v_add_f32_e32 v54, v56, v57
	v_add_f32_e32 v56, v58, v59
	s_waitcnt vmcnt(0)
	v_mov_b32_e32 v55, v62
	v_mov_b32_e32 v57, v63
	v_pk_add_f32 v[48:49], v[68:69], v[48:49]
	v_pk_add_f32 v[50:51], v[50:51], v[52:53]
	v_pk_add_f32 v[52:53], v[54:55], v[56:57]
	v_add_f32_e32 v54, v48, v49
	v_pk_add_f32 v[48:49], v[50:51], v[50:51] op_sel:[0,1] op_sel_hi:[1,0]
	v_mov_b32_e32 v59, v60
	v_add_f32_e32 v58, 0, v54
	v_mov_b32_e32 v49, v61
	v_pk_add_f32 v[48:49], v[58:59], v[48:49]
	v_lshlrev_b64 v[50:51], 6, v[64:65]
	v_pk_add_f32 v[48:49], v[48:49], v[52:53]
	v_lshl_add_u64 v[50:51], s[18:19], 0, v[50:51]
	v_add_f32_e32 v48, v48, v49
	v_fmamk_f32 v48, v48, 0x3a800000, v161
	v_mul_f32_e32 v49, 0x4b800000, v48
	v_cmp_gt_f32_e32 vcc, s57, v48
	s_nop 1
	v_cndmask_b32_e32 v48, v48, v49, vcc
	v_rsq_f32_e32 v52, v48
	v_lshl_add_u64 v[48:49], v[66:67], 0, v[146:147]
	v_mul_f32_e32 v53, 0x45800000, v52
	v_cndmask_b32_e32 v52, v52, v53, vcc
	v_pk_mul_f32 v[44:45], v[44:45], v[52:53] op_sel_hi:[1,0]
	v_pk_mul_f32 v[46:47], v[46:47], v[52:53] op_sel_hi:[1,0]
	v_pk_mul_f32 v[40:41], v[40:41], v[52:53] op_sel_hi:[1,0]
	v_pk_mul_f32 v[42:43], v[42:43], v[52:53] op_sel_hi:[1,0]
	v_pk_mul_f32 v[36:37], v[36:37], v[52:53] op_sel_hi:[1,0]
	v_pk_mul_f32 v[38:39], v[38:39], v[52:53] op_sel_hi:[1,0]
	v_pk_mul_f32 v[32:33], v[32:33], v[52:53] op_sel_hi:[1,0]
	v_pk_mul_f32 v[34:35], v[34:35], v[52:53] op_sel_hi:[1,0]
	v_mul_f32_e32 v52, 0xbfb8aa3b, v44
	v_mul_f32_e32 v53, 0xbfb8aa3b, v45
	v_mul_f32_e32 v54, 0xbfb8aa3b, v46
	v_mul_f32_e32 v55, 0xbfb8aa3b, v47
	v_mul_f32_e32 v56, 0xbfb8aa3b, v40
	v_mul_f32_e32 v57, 0xbfb8aa3b, v41
	v_mul_f32_e32 v58, 0xbfb8aa3b, v42
	v_mul_f32_e32 v59, 0xbfb8aa3b, v43
	v_exp_f32_e32 v52, v52
	v_exp_f32_e32 v53, v53
	v_exp_f32_e32 v54, v54
	v_exp_f32_e32 v55, v55
	v_exp_f32_e32 v56, v56
	v_exp_f32_e32 v57, v57
	v_exp_f32_e32 v58, v58
	v_exp_f32_e32 v59, v59
	v_add_f32_e32 v52, 1.0, v52
	v_add_f32_e32 v53, 1.0, v53
	v_add_f32_e32 v54, 1.0, v54
	v_add_f32_e32 v55, 1.0, v55
	v_add_f32_e32 v56, 1.0, v56
	v_add_f32_e32 v57, 1.0, v57
	v_add_f32_e32 v58, 1.0, v58
	v_add_f32_e32 v59, 1.0, v59
	v_rcp_f32_e32 v52, v52
	v_rcp_f32_e32 v53, v53
	v_rcp_f32_e32 v54, v54
	v_rcp_f32_e32 v55, v55
	v_rcp_f32_e32 v56, v56
	v_rcp_f32_e32 v57, v57
	v_rcp_f32_e32 v58, v58
	v_rcp_f32_e32 v59, v59
	v_pk_mul_f32 v[44:45], v[44:45], v[52:53]
	v_pk_mul_f32 v[46:47], v[46:47], v[54:55]
	v_pk_mul_f32 v[40:41], v[40:41], v[56:57]
	v_pk_mul_f32 v[42:43], v[42:43], v[58:59]
	v_pk_mul_f32 v[36:37], v[36:37], v[44:45]
	v_pk_mul_f32 v[38:39], v[38:39], v[46:47]
	v_pk_mul_f32 v[40:41], v[32:33], v[40:41]
	v_pk_mul_f32 v[42:43], v[34:35], v[42:43]
	v_cvt_pk_bf16_f32 v32, v36, v37
	v_cvt_pk_bf16_f32 v33, v38, v39
	v_cvt_pk_bf16_f32 v34, v40, v41
	v_cvt_pk_bf16_f32 v35, v42, v43
	global_store_dwordx4 v[48:49], v[32:35], off sc1
	global_load_dwordx4 v[32:35], v[50:51], off
	s_nop 0
	global_load_dwordx4 v[36:39], v[50:51], off offset:16
	global_load_dwordx4 v[40:43], v[50:51], off offset:32
	global_load_dwordx4 v[44:47], v[50:51], off offset:48
	v_add_u32_e32 v48, 0xb0, v148
	v_mad_i64_i32 v[50:51], s[8:9], v64, s58, v[144:145]
	v_ashrrev_i32_e32 v49, 31, v48
	s_waitcnt vmcnt(3)
	v_mov_b32_e32 v52, v33
	v_mov_b32_e32 v53, v34
	v_mov_b32_e32 v33, v35
	s_waitcnt vmcnt(2)
	v_mov_b32_e32 v34, v37
	v_mov_b32_e32 v35, v38
	v_mov_b32_e32 v37, v39
	s_waitcnt vmcnt(1)
	v_add_f32_e32 v38, v40, v41
	v_add_f32_e32 v40, v42, v43
	s_waitcnt vmcnt(0)
; #define PG8_BAR __builtin_amdgcn_s_barrier()
; __device__ __forceinline__ float sigmoidf_(float v) { return __builtin_amdgcn_rcpf(1.f + __builtin_amdgcn_exp2f(-v * LOG2E)); }
; __device__ __forceinline__ v4u pack8(f32x4 a, f32x4 b) { v4u r; r.x = cvt_pk_bf16(a[0], a[1]); r.y = cvt_pk_bf16(a[2], a[3]); r.z = cvt_pk_bf16(b[0], b[1]); r.w = cvt_pk_bf16(b[2], b[3]); return r; }
; template <class Epi, class Sched, bool ALIGN_EPI = false, bool SP2 = false>
; __device__ __forceinline__ void gemm_phase(PG8_LAS unsigned char* lds, const Gemm g, const Sched& S, const Epi& E) {
;     ...
;         if (!has_next) break;
; #pragma unroll
;         for (int a = 0; a < 2; ++a)
; #pragma unroll
;             for (int b = 0; b < 2; ++b)
; #pragma unroll
;                 for (int m = 0; m < 4; ++m)
; #pragma unroll
;                     for (int n = 0; n < 2; ++n) acc[a][b][m][n] = (f32x4){0.f, 0.f, 0.f, 0.f};
;         cur = nxt; cA = nA; cB = nB; ++ui;
;         if constexpr (ALIGN_EPI) { if (wr == 1) PG8_BAR; }
;     __device__ __forceinline__ void operator()(const f32x4 (&acc)[2][2][4][2], const Unit& u, int wr, int wc, int fr, int fq) const {
;     ...
;         for (int ai = 0; ai < 2; ++ai)
; #pragma unroll
;             for (int m = 0; m < 4; ++m) {
;                 const int row = row0 + ai * 128 + m * 16;
;                 float sq = 0.f;
; #pragma unroll
;                 for (int k = 0; k < 4; ++k) { const f32x4 p = *(const f32x4*)(ss1 + (size_t)row * 16 + 4 * k); sq += (p[0] + p[1]) + (p[2] + p[3]); }
;                 const float rs = rsqrtf(sq * (1.f / 1024.f) + EPS);
;                 f32x4 o[2];
; #pragma unroll
;                 for (int n = 0; n < 2; ++n) {
;                     const f32x4 g = acc[ai][0][m][n] * rs, up = acc[ai][1][m][n] * rs;
; #pragma unroll
;                     for (int j = 0; j < 4; ++j) o[n][j] = g[j] * sigmoidf_(g[j]) * up[j];
;                 }
;                 *(v4u*)(H + (size_t)row * FF + col0) = pack8(o[0], o[1]);
;             }
	v_mov_b32_e32 v39, v46
	v_mov_b32_e32 v41, v47
	v_pk_add_f32 v[32:33], v[52:53], v[32:33]
	v_pk_add_f32 v[34:35], v[34:35], v[36:37]
	v_pk_add_f32 v[36:37], v[38:39], v[40:41]
	v_add_f32_e32 v38, v32, v33
	v_pk_add_f32 v[32:33], v[34:35], v[34:35] op_sel:[0,1] op_sel_hi:[1,0]
	v_mov_b32_e32 v43, v44
	v_add_f32_e32 v42, 0, v38
	v_mov_b32_e32 v33, v45
	v_pk_add_f32 v[32:33], v[42:43], v[32:33]
	v_lshlrev_b64 v[34:35], 6, v[48:49]
	v_pk_add_f32 v[32:33], v[32:33], v[36:37]
	v_lshl_add_u64 v[34:35], s[18:19], 0, v[34:35]
	v_add_f32_e32 v32, v32, v33
	v_fmamk_f32 v32, v32, 0x3a800000, v161
	v_mul_f32_e32 v33, 0x4b800000, v32
	v_cmp_gt_f32_e32 vcc, s57, v32
	s_nop 1
	v_cndmask_b32_e32 v32, v32, v33, vcc
	v_rsq_f32_e32 v36, v32
	v_lshl_add_u64 v[32:33], v[50:51], 0, v[146:147]
	v_mul_f32_e32 v37, 0x45800000, v36
	v_cndmask_b32_e32 v36, v36, v37, vcc
	v_pk_mul_f32 v[28:29], v[28:29], v[36:37] op_sel_hi:[1,0]
	v_pk_mul_f32 v[30:31], v[30:31], v[36:37] op_sel_hi:[1,0]
	v_pk_mul_f32 v[24:25], v[24:25], v[36:37] op_sel_hi:[1,0]
	v_pk_mul_f32 v[26:27], v[26:27], v[36:37] op_sel_hi:[1,0]
	v_pk_mul_f32 v[20:21], v[20:21], v[36:37] op_sel_hi:[1,0]
	v_pk_mul_f32 v[22:23], v[22:23], v[36:37] op_sel_hi:[1,0]
	v_pk_mul_f32 v[16:17], v[16:17], v[36:37] op_sel_hi:[1,0]
	v_pk_mul_f32 v[18:19], v[18:19], v[36:37] op_sel_hi:[1,0]
	v_mul_f32_e32 v36, 0xbfb8aa3b, v28
	v_mul_f32_e32 v37, 0xbfb8aa3b, v29
	v_mul_f32_e32 v38, 0xbfb8aa3b, v30
	v_mul_f32_e32 v39, 0xbfb8aa3b, v31
	v_mul_f32_e32 v40, 0xbfb8aa3b, v24
	v_mul_f32_e32 v41, 0xbfb8aa3b, v25
	v_mul_f32_e32 v42, 0xbfb8aa3b, v26
	v_mul_f32_e32 v43, 0xbfb8aa3b, v27
	v_exp_f32_e32 v36, v36
	v_exp_f32_e32 v37, v37
	v_exp_f32_e32 v38, v38
	v_exp_f32_e32 v39, v39
	v_exp_f32_e32 v40, v40
	v_exp_f32_e32 v41, v41
	v_exp_f32_e32 v42, v42
	v_exp_f32_e32 v43, v43
	v_add_f32_e32 v36, 1.0, v36
	v_add_f32_e32 v37, 1.0, v37
	v_add_f32_e32 v38, 1.0, v38
	v_add_f32_e32 v39, 1.0, v39
	v_add_f32_e32 v40, 1.0, v40
	v_add_f32_e32 v41, 1.0, v41
	v_add_f32_e32 v42, 1.0, v42
	v_add_f32_e32 v43, 1.0, v43
	v_rcp_f32_e32 v36, v36
	v_rcp_f32_e32 v37, v37
	v_rcp_f32_e32 v38, v38
	v_rcp_f32_e32 v39, v39
	v_rcp_f32_e32 v40, v40
	v_rcp_f32_e32 v41, v41
	v_rcp_f32_e32 v42, v42
	v_rcp_f32_e32 v43, v43
	v_pk_mul_f32 v[28:29], v[28:29], v[36:37]
	v_pk_mul_f32 v[30:31], v[30:31], v[38:39]
	v_pk_mul_f32 v[24:25], v[24:25], v[40:41]
	v_pk_mul_f32 v[26:27], v[26:27], v[42:43]
	v_pk_mul_f32 v[20:21], v[20:21], v[28:29]
	v_pk_mul_f32 v[22:23], v[22:23], v[30:31]
	v_pk_mul_f32 v[24:25], v[16:17], v[24:25]
	v_pk_mul_f32 v[26:27], v[18:19], v[26:27]
	v_cvt_pk_bf16_f32 v16, v20, v21
	v_cvt_pk_bf16_f32 v17, v22, v23
	v_cvt_pk_bf16_f32 v18, v24, v25
	v_cvt_pk_bf16_f32 v19, v26, v27
	global_store_dwordx4 v[32:33], v[16:19], off sc1
	global_load_dwordx4 v[16:19], v[34:35], off
	s_nop 0
	global_load_dwordx4 v[20:23], v[34:35], off offset:16
	global_load_dwordx4 v[24:27], v[34:35], off offset:32
	global_load_dwordx4 v[28:31], v[34:35], off offset:48
	s_andn2_b64 vcc, exec, s[6:7]
	s_mov_b64 s[6:7], -1
	s_waitcnt vmcnt(3)
	v_mov_b32_e32 v32, v17
	v_mov_b32_e32 v33, v18
	v_mov_b32_e32 v17, v19
	s_waitcnt vmcnt(2)
	v_mov_b32_e32 v18, v21
	v_mov_b32_e32 v19, v22
	v_mov_b32_e32 v21, v23
	s_waitcnt vmcnt(1)
	v_add_f32_e32 v22, v24, v25
	v_add_f32_e32 v24, v26, v27
	s_waitcnt vmcnt(0)
	v_mov_b32_e32 v23, v30
	v_mov_b32_e32 v25, v31
	v_pk_add_f32 v[16:17], v[32:33], v[16:17]
	v_pk_add_f32 v[18:19], v[18:19], v[20:21]
	v_pk_add_f32 v[20:21], v[22:23], v[24:25]
	v_add_f32_e32 v22, v16, v17
	v_pk_add_f32 v[16:17], v[18:19], v[18:19] op_sel:[0,1] op_sel_hi:[1,0]
	v_mov_b32_e32 v27, v28
	v_add_f32_e32 v26, 0, v22
	v_mov_b32_e32 v17, v29
	v_pk_add_f32 v[16:17], v[26:27], v[16:17]
	s_nop 0
	v_pk_add_f32 v[16:17], v[16:17], v[20:21]
	s_nop 0
	v_add_f32_e32 v16, v16, v17
	v_fmamk_f32 v16, v16, 0x3a800000, v161
	v_mul_f32_e32 v17, 0x4b800000, v16
	v_cmp_gt_f32_e64 s[8:9], s57, v16
	s_nop 1
	v_cndmask_b32_e64 v16, v16, v17, s[8:9]
	v_rsq_f32_e32 v18, v16
	v_mad_i64_i32 v[16:17], s[46:47], v48, s58, v[144:145]
	v_lshl_add_u64 v[16:17], v[16:17], 0, v[146:147]
	v_mul_f32_e32 v19, 0x45800000, v18
	v_cndmask_b32_e64 v18, v18, v19, s[8:9]
	v_pk_mul_f32 v[12:13], v[12:13], v[18:19] op_sel_hi:[1,0]
	v_pk_mul_f32 v[14:15], v[14:15], v[18:19] op_sel_hi:[1,0]
	v_pk_mul_f32 v[8:9], v[8:9], v[18:19] op_sel_hi:[1,0]
	v_pk_mul_f32 v[10:11], v[10:11], v[18:19] op_sel_hi:[1,0]
	v_pk_mul_f32 v[4:5], v[4:5], v[18:19] op_sel_hi:[1,0]
	v_pk_mul_f32 v[6:7], v[6:7], v[18:19] op_sel_hi:[1,0]
	v_pk_mul_f32 v[0:1], v[0:1], v[18:19] op_sel_hi:[1,0]
	v_pk_mul_f32 v[2:3], v[2:3], v[18:19] op_sel_hi:[1,0]
	v_mul_f32_e32 v18, 0xbfb8aa3b, v12
	v_mul_f32_e32 v19, 0xbfb8aa3b, v13
	v_mul_f32_e32 v20, 0xbfb8aa3b, v14
	v_mul_f32_e32 v21, 0xbfb8aa3b, v15
	v_mul_f32_e32 v22, 0xbfb8aa3b, v8
	v_mul_f32_e32 v23, 0xbfb8aa3b, v9
	v_mul_f32_e32 v24, 0xbfb8aa3b, v10
	v_mul_f32_e32 v25, 0xbfb8aa3b, v11
	v_exp_f32_e32 v18, v18
	v_exp_f32_e32 v19, v19
	v_exp_f32_e32 v20, v20
	v_exp_f32_e32 v21, v21
	v_exp_f32_e32 v22, v22
	v_exp_f32_e32 v23, v23
	v_exp_f32_e32 v24, v24
	v_exp_f32_e32 v25, v25
	v_add_f32_e32 v18, 1.0, v18
	v_add_f32_e32 v19, 1.0, v19
	v_add_f32_e32 v20, 1.0, v20
	v_add_f32_e32 v21, 1.0, v21
	v_add_f32_e32 v22, 1.0, v22
	v_add_f32_e32 v23, 1.0, v23
	v_add_f32_e32 v24, 1.0, v24
	v_add_f32_e32 v25, 1.0, v25
	v_rcp_f32_e32 v18, v18
	v_rcp_f32_e32 v19, v19
	v_rcp_f32_e32 v20, v20
	v_rcp_f32_e32 v21, v21
	v_rcp_f32_e32 v22, v22
	v_rcp_f32_e32 v23, v23
	v_rcp_f32_e32 v24, v24
	v_rcp_f32_e32 v25, v25
	v_pk_mul_f32 v[12:13], v[12:13], v[18:19]
	v_pk_mul_f32 v[14:15], v[14:15], v[20:21]
	v_pk_mul_f32 v[8:9], v[8:9], v[22:23]
	v_pk_mul_f32 v[10:11], v[10:11], v[24:25]
	v_pk_mul_f32 v[4:5], v[4:5], v[12:13]
	v_pk_mul_f32 v[6:7], v[6:7], v[14:15]
	v_pk_mul_f32 v[8:9], v[0:1], v[8:9]
	v_pk_mul_f32 v[10:11], v[2:3], v[10:11]
	v_cvt_pk_bf16_f32 v0, v4, v5
	v_cvt_pk_bf16_f32 v1, v6, v7
	v_cvt_pk_bf16_f32 v2, v8, v9
	v_cvt_pk_bf16_f32 v3, v10, v11
	global_store_dwordx4 v[16:17], v[0:3], off sc1
	s_cbranch_vccnz .LBB0_1474
	s_andn2_b64 vcc, exec, s[10:11]
	s_cbranch_vccnz .LBB0_1473
	s_barrier
	s_branch .LBB0_1473
